# v30 + P6 epilogue: the two s_waitcnt vmcnt(0) guarding the header-issued row-statistics loads relaxed to vmcnt(8) (those loads are older than the 8 LDS-DMA prefetches the K-loop leaves in flight)
# speedup vs baseline: 1.0004x; 1.0004x over previous
.LBB0_1117:
	v_mov_b32_e32 v150, v0
	s_movk_i32 s8, 0x100
	v_and_b32_e32 v149, 15, v150
	v_and_b32_e32 v151, 48, v150
	v_or3_b32 v151, v151, s52, v149
	v_cmp_gt_i32_e32 vcc, s8, v151
	s_and_saveexec_b64 s[8:9], vcc
	s_cbranch_execz .LBB0_1119
	s_waitcnt vmcnt(8)
	v_mov_b32_e32 v152, v120
	v_mov_b32_e32 v153, v116
	v_mov_b32_e32 v116, v121
	v_mov_b32_e32 v120, v122
	v_mov_b32_e32 v121, v118
	v_mov_b32_e32 v118, v123
	v_pk_add_f32 v[116:117], v[152:153], v[116:117]
	v_pk_add_f32 v[118:119], v[120:121], v[118:119]
	s_nop 0
	v_pk_add_f32 v[116:117], v[116:117], v[118:119]
	s_nop 0
	v_add_f32_e32 v116, v116, v117
	v_fmamk_f32 v116, v116, 0x3a000000, v214
	v_rsq_f32_e32 v116, v116
	v_lshl_add_u32 v117, v151, 2, 0
	v_add_u32_e32 v117, 0x20400, v117
	ds_write_b32 v117, v116
.LBB0_1119:
	s_or_b64 exec, exec, s[8:9]
	s_add_i32 s11, s11, s46
	s_waitcnt vmcnt(8)
	v_bfe_u32 v117, v150, 2, 4
	v_or_b32_e32 v121, s11, v117
	s_lshl_b32 s8, s12, 7
	v_lshlrev_b32_e32 v117, 3, v149
	v_and_or_b32 v117, v117, 24, s8
	v_and_b32_e32 v116, 63, v150
	v_or_b32_e32 v118, s47, v117
	v_lshlrev_b32_e32 v117, 6, v149
	s_movk_i32 s8, 0xfc
	v_bitop3_b32 v120, v117, s8, v116 bitop3:0xc8
	v_readlane_b32 s8, v255, 5
	v_readlane_b32 s9, v255, 6
	v_ashrrev_i32_e32 v119, 31, v118
	s_movk_i32 s11, 0x2c00
	v_mov_b64_e32 v[116:117], s[8:9]
	v_mad_i64_i32 v[122:123], s[8:9], v121, s11, v[116:117]
	v_lshlrev_b64 v[118:119], 1, v[118:119]
	s_waitcnt lgkmcnt(0)
	s_barrier
	v_lshl_add_u64 v[150:151], v[122:123], 0, v[118:119]
	v_lshl_add_u32 v122, v149, 2, s51
	ds_read_b32 v123, v122
	v_pk_mul_f32 v[130:131], v[126:127], v[130:131]
	v_pk_mul_f32 v[138:139], v[134:135], v[138:139]
	v_pk_mul_f32 v[136:137], v[132:133], v[136:137]
	v_pk_mul_f32 v[128:129], v[124:125], v[128:129]
	s_waitcnt lgkmcnt(0)
	v_mul_f32_e32 v152, 0xbfb8aa3b, v123
	v_pk_mul_f32 v[126:127], v[126:127], v[152:153] op_sel_hi:[1,0]
	v_pk_mul_f32 v[132:133], v[132:133], v[152:153] op_sel_hi:[1,0]
	v_pk_mul_f32 v[134:135], v[134:135], v[152:153] op_sel_hi:[1,0]
	v_pk_mul_f32 v[124:125], v[124:125], v[152:153] op_sel_hi:[1,0]
	v_exp_f32_e32 v126, v126
	v_exp_f32_e32 v127, v127
	v_exp_f32_e32 v132, v132
	v_exp_f32_e32 v133, v133
	v_exp_f32_e32 v134, v134
	v_exp_f32_e32 v135, v135
	v_exp_f32_e32 v124, v124
	v_exp_f32_e32 v125, v125
	v_pk_add_f32 v[126:127], v[126:127], 1.0 op_sel_hi:[1,0]
	v_pk_add_f32 v[132:133], v[132:133], 1.0 op_sel_hi:[1,0]
	v_pk_add_f32 v[134:135], v[134:135], 1.0 op_sel_hi:[1,0]
	v_pk_add_f32 v[124:125], v[124:125], 1.0 op_sel_hi:[1,0]
	v_rcp_f32_e32 v126, v126
	v_rcp_f32_e32 v127, v127
	v_rcp_f32_e32 v132, v132
	v_rcp_f32_e32 v133, v133
	v_rcp_f32_e32 v134, v134
	v_rcp_f32_e32 v135, v135
	v_rcp_f32_e32 v124, v124
	v_rcp_f32_e32 v125, v125
	v_mul_f32_e32 v154, v123, v123
	v_pk_mul_f32 v[126:127], v[154:155], v[126:127] op_sel_hi:[0,1]
	v_pk_mul_f32 v[132:133], v[154:155], v[132:133] op_sel_hi:[0,1]
	v_pk_mul_f32 v[134:135], v[154:155], v[134:135] op_sel_hi:[0,1]
	v_pk_mul_f32 v[124:125], v[154:155], v[124:125] op_sel_hi:[0,1]
	v_pk_mul_f32 v[126:127], v[130:131], v[126:127]
	v_pk_mul_f32 v[132:133], v[136:137], v[132:133]
	v_pk_mul_f32 v[134:135], v[138:139], v[134:135]
	v_pk_mul_f32 v[124:125], v[128:129], v[124:125]
	v_cvt_pk_bf16_f32 v123, v132, v133
	v_cvt_pk_bf16_f32 v128, v134, v135
	v_pk_mul_f32 v[106:107], v[102:103], v[106:107]
	v_cvt_pk_bf16_f32 v129, v124, v125
	v_cvt_pk_bf16_f32 v127, v126, v127
	ds_bpermute_b32 v124, v120, v123
	ds_bpermute_b32 v125, v120, v128
	ds_bpermute_b32 v126, v120, v129
	ds_bpermute_b32 v127, v120, v127
	v_or_b32_e32 v123, 16, v121
	v_pk_mul_f32 v[114:115], v[110:111], v[114:115]
	v_pk_mul_f32 v[112:113], v[108:109], v[112:113]
	v_pk_mul_f32 v[104:105], v[100:101], v[104:105]
	s_waitcnt lgkmcnt(0)
	global_store_dwordx4 v[150:151], v[124:127], off
	v_pk_mul_f32 v[90:91], v[86:87], v[90:91]
	v_pk_mul_f32 v[98:99], v[94:95], v[98:99]
	v_mad_i64_i32 v[124:125], s[8:9], v123, s11, v[116:117]
	ds_read_b32 v123, v122 offset:64
	v_lshl_add_u64 v[124:125], v[124:125], 0, v[118:119]
	v_pk_mul_f32 v[96:97], v[92:93], v[96:97]
	v_pk_mul_f32 v[88:89], v[84:85], v[88:89]
	v_pk_mul_f32 v[74:75], v[70:71], v[74:75]
	s_waitcnt lgkmcnt(0)
	v_mul_f32_e32 v126, 0xbfb8aa3b, v123
	v_pk_mul_f32 v[102:103], v[102:103], v[126:127] op_sel_hi:[1,0]
	v_pk_mul_f32 v[108:109], v[108:109], v[126:127] op_sel_hi:[1,0]
	v_pk_mul_f32 v[110:111], v[110:111], v[126:127] op_sel_hi:[1,0]
	v_pk_mul_f32 v[100:101], v[100:101], v[126:127] op_sel_hi:[1,0]
	v_exp_f32_e32 v102, v102
	v_exp_f32_e32 v103, v103
	v_exp_f32_e32 v108, v108
	v_exp_f32_e32 v109, v109
	v_exp_f32_e32 v110, v110
	v_exp_f32_e32 v111, v111
	v_exp_f32_e32 v100, v100
	v_exp_f32_e32 v101, v101
	v_pk_add_f32 v[102:103], v[102:103], 1.0 op_sel_hi:[1,0]
	v_pk_add_f32 v[108:109], v[108:109], 1.0 op_sel_hi:[1,0]
	v_pk_add_f32 v[110:111], v[110:111], 1.0 op_sel_hi:[1,0]
	v_pk_add_f32 v[100:101], v[100:101], 1.0 op_sel_hi:[1,0]
	v_rcp_f32_e32 v102, v102
	v_rcp_f32_e32 v103, v103
	v_rcp_f32_e32 v108, v108
	v_rcp_f32_e32 v109, v109
	v_rcp_f32_e32 v110, v110
	v_rcp_f32_e32 v111, v111
	v_rcp_f32_e32 v100, v100
	v_rcp_f32_e32 v101, v101
	v_mul_f32_e32 v128, v123, v123
	v_pk_mul_f32 v[102:103], v[128:129], v[102:103] op_sel_hi:[0,1]
	v_pk_mul_f32 v[108:109], v[128:129], v[108:109] op_sel_hi:[0,1]
	v_pk_mul_f32 v[110:111], v[128:129], v[110:111] op_sel_hi:[0,1]
	v_pk_mul_f32 v[100:101], v[128:129], v[100:101] op_sel_hi:[0,1]
	v_pk_mul_f32 v[102:103], v[106:107], v[102:103]
	v_pk_mul_f32 v[108:109], v[112:113], v[108:109]
	v_pk_mul_f32 v[110:111], v[114:115], v[110:111]
	v_pk_mul_f32 v[100:101], v[104:105], v[100:101]
	v_cvt_pk_bf16_f32 v104, v108, v109
	v_cvt_pk_bf16_f32 v105, v110, v111
	v_pk_mul_f32 v[82:83], v[78:79], v[82:83]
	v_cvt_pk_bf16_f32 v106, v100, v101
	v_cvt_pk_bf16_f32 v103, v102, v103
	ds_bpermute_b32 v100, v120, v104
	ds_bpermute_b32 v101, v120, v105
	ds_bpermute_b32 v102, v120, v106
	ds_bpermute_b32 v103, v120, v103
	v_pk_mul_f32 v[80:81], v[76:77], v[80:81]
	v_pk_mul_f32 v[72:73], v[68:69], v[72:73]
	v_pk_mul_f32 v[58:59], v[54:55], v[58:59]
	v_pk_mul_f32 v[66:67], v[62:63], v[66:67]
	s_waitcnt lgkmcnt(0)
	global_store_dwordx4 v[124:125], v[100:103], off
	ds_read_b32 v103, v122 offset:128
	v_pk_mul_f32 v[64:65], v[60:61], v[64:65]
	v_or_b32_e32 v100, 32, v121
	v_mad_i64_i32 v[100:101], s[8:9], v100, s11, v[116:117]
	s_waitcnt lgkmcnt(0)
	v_mul_f32_e32 v102, 0xbfb8aa3b, v103
	v_pk_mul_f32 v[86:87], v[86:87], v[102:103] op_sel_hi:[1,0]
	v_pk_mul_f32 v[92:93], v[92:93], v[102:103] op_sel_hi:[1,0]
	v_pk_mul_f32 v[94:95], v[94:95], v[102:103] op_sel_hi:[1,0]
	v_pk_mul_f32 v[84:85], v[84:85], v[102:103] op_sel_hi:[1,0]
	v_exp_f32_e32 v86, v86
	v_exp_f32_e32 v87, v87
	v_exp_f32_e32 v92, v92
	v_exp_f32_e32 v93, v93
	v_exp_f32_e32 v94, v94
	v_exp_f32_e32 v95, v95
	v_exp_f32_e32 v84, v84
	v_exp_f32_e32 v85, v85
	v_pk_add_f32 v[86:87], v[86:87], 1.0 op_sel_hi:[1,0]
	v_pk_add_f32 v[92:93], v[92:93], 1.0 op_sel_hi:[1,0]
	v_pk_add_f32 v[94:95], v[94:95], 1.0 op_sel_hi:[1,0]
	v_pk_add_f32 v[84:85], v[84:85], 1.0 op_sel_hi:[1,0]
	v_rcp_f32_e32 v86, v86
	v_rcp_f32_e32 v87, v87
	v_rcp_f32_e32 v92, v92
	v_rcp_f32_e32 v93, v93
	v_rcp_f32_e32 v94, v94
	v_rcp_f32_e32 v95, v95
	v_rcp_f32_e32 v84, v84
	v_rcp_f32_e32 v85, v85
	v_mul_f32_e32 v104, v103, v103
	v_pk_mul_f32 v[86:87], v[104:105], v[86:87] op_sel_hi:[0,1]
	v_pk_mul_f32 v[92:93], v[104:105], v[92:93] op_sel_hi:[0,1]
	v_pk_mul_f32 v[94:95], v[104:105], v[94:95] op_sel_hi:[0,1]
	v_pk_mul_f32 v[84:85], v[104:105], v[84:85] op_sel_hi:[0,1]
	v_pk_mul_f32 v[86:87], v[90:91], v[86:87]
	v_pk_mul_f32 v[92:93], v[96:97], v[92:93]
	v_pk_mul_f32 v[94:95], v[98:99], v[94:95]
	v_pk_mul_f32 v[84:85], v[88:89], v[84:85]
	v_cvt_pk_bf16_f32 v88, v92, v93
	v_cvt_pk_bf16_f32 v89, v94, v95
	v_lshl_add_u64 v[100:101], v[100:101], 0, v[118:119]
	v_cvt_pk_bf16_f32 v90, v84, v85
	v_cvt_pk_bf16_f32 v87, v86, v87
	ds_bpermute_b32 v84, v120, v88
	ds_bpermute_b32 v85, v120, v89
	ds_bpermute_b32 v86, v120, v90
	ds_bpermute_b32 v87, v120, v87
	v_pk_mul_f32 v[56:57], v[52:53], v[56:57]
	v_pk_mul_f32 v[42:43], v[38:39], v[42:43]
	v_pk_mul_f32 v[50:51], v[46:47], v[50:51]
	v_pk_mul_f32 v[48:49], v[44:45], v[48:49]
	s_waitcnt lgkmcnt(0)
	global_store_dwordx4 v[100:101], v[84:87], off
	ds_read_b32 v87, v122 offset:192
	v_pk_mul_f32 v[40:41], v[36:37], v[40:41]
	v_or_b32_e32 v84, 48, v121
	v_mad_i64_i32 v[84:85], s[8:9], v84, s11, v[116:117]
	s_waitcnt lgkmcnt(0)
	v_mul_f32_e32 v86, 0xbfb8aa3b, v87
	v_pk_mul_f32 v[70:71], v[70:71], v[86:87] op_sel_hi:[1,0]
	v_pk_mul_f32 v[76:77], v[76:77], v[86:87] op_sel_hi:[1,0]
	v_pk_mul_f32 v[78:79], v[78:79], v[86:87] op_sel_hi:[1,0]
	v_pk_mul_f32 v[68:69], v[68:69], v[86:87] op_sel_hi:[1,0]
	v_exp_f32_e32 v70, v70
	v_exp_f32_e32 v71, v71
	v_exp_f32_e32 v76, v76
	v_exp_f32_e32 v77, v77
	v_exp_f32_e32 v78, v78
	v_exp_f32_e32 v79, v79
	v_exp_f32_e32 v68, v68
	v_exp_f32_e32 v69, v69
	v_pk_add_f32 v[70:71], v[70:71], 1.0 op_sel_hi:[1,0]
	v_pk_add_f32 v[76:77], v[76:77], 1.0 op_sel_hi:[1,0]
	v_pk_add_f32 v[78:79], v[78:79], 1.0 op_sel_hi:[1,0]
	v_pk_add_f32 v[68:69], v[68:69], 1.0 op_sel_hi:[1,0]
	v_rcp_f32_e32 v70, v70
	v_rcp_f32_e32 v71, v71
	v_rcp_f32_e32 v76, v76
	v_rcp_f32_e32 v77, v77
	v_rcp_f32_e32 v78, v78
	v_rcp_f32_e32 v79, v79
	v_rcp_f32_e32 v68, v68
	v_rcp_f32_e32 v69, v69
	v_mul_f32_e32 v88, v87, v87
	v_pk_mul_f32 v[70:71], v[88:89], v[70:71] op_sel_hi:[0,1]
	v_pk_mul_f32 v[76:77], v[88:89], v[76:77] op_sel_hi:[0,1]
	v_pk_mul_f32 v[78:79], v[88:89], v[78:79] op_sel_hi:[0,1]
	v_pk_mul_f32 v[68:69], v[88:89], v[68:69] op_sel_hi:[0,1]
	v_pk_mul_f32 v[70:71], v[74:75], v[70:71]
	v_pk_mul_f32 v[76:77], v[80:81], v[76:77]
	v_pk_mul_f32 v[78:79], v[82:83], v[78:79]
	v_pk_mul_f32 v[68:69], v[72:73], v[68:69]
	v_cvt_pk_bf16_f32 v72, v76, v77
	v_cvt_pk_bf16_f32 v73, v78, v79
	v_lshl_add_u64 v[84:85], v[84:85], 0, v[118:119]
	v_cvt_pk_bf16_f32 v74, v68, v69
	v_cvt_pk_bf16_f32 v71, v70, v71
	ds_bpermute_b32 v68, v120, v72
	ds_bpermute_b32 v69, v120, v73
	ds_bpermute_b32 v70, v120, v74
	ds_bpermute_b32 v71, v120, v71
	v_pk_mul_f32 v[24:25], v[20:21], v[24:25]
	v_pk_mul_f32 v[32:33], v[28:29], v[32:33]
	v_pk_mul_f32 v[30:31], v[26:27], v[30:31]
	v_pk_mul_f32 v[22:23], v[18:19], v[22:23]
	s_waitcnt lgkmcnt(0)
	global_store_dwordx4 v[84:85], v[68:71], off
	ds_read_b32 v71, v122 offset:512
	v_pk_mul_f32 v[2:3], v[6:7], v[2:3]
	v_add_u32_e32 v68, 0x80, v121
	v_mad_i64_i32 v[68:69], s[8:9], v68, s11, v[116:117]
	s_waitcnt lgkmcnt(0)
	v_mul_f32_e32 v70, 0xbfb8aa3b, v71
	v_pk_mul_f32 v[54:55], v[54:55], v[70:71] op_sel_hi:[1,0]
	v_pk_mul_f32 v[60:61], v[60:61], v[70:71] op_sel_hi:[1,0]
	v_pk_mul_f32 v[62:63], v[62:63], v[70:71] op_sel_hi:[1,0]
	v_pk_mul_f32 v[52:53], v[52:53], v[70:71] op_sel_hi:[1,0]
	v_exp_f32_e32 v54, v54
	v_exp_f32_e32 v55, v55
	v_exp_f32_e32 v60, v60
	v_exp_f32_e32 v61, v61
	v_exp_f32_e32 v62, v62
	v_exp_f32_e32 v63, v63
	v_exp_f32_e32 v52, v52
	v_exp_f32_e32 v53, v53
	v_pk_add_f32 v[54:55], v[54:55], 1.0 op_sel_hi:[1,0]
	v_pk_add_f32 v[60:61], v[60:61], 1.0 op_sel_hi:[1,0]
	v_pk_add_f32 v[62:63], v[62:63], 1.0 op_sel_hi:[1,0]
	v_pk_add_f32 v[52:53], v[52:53], 1.0 op_sel_hi:[1,0]
	v_rcp_f32_e32 v54, v54
	v_rcp_f32_e32 v55, v55
	v_rcp_f32_e32 v60, v60
	v_rcp_f32_e32 v61, v61
	v_rcp_f32_e32 v62, v62
	v_rcp_f32_e32 v63, v63
	v_rcp_f32_e32 v52, v52
	v_rcp_f32_e32 v53, v53
	v_mul_f32_e32 v72, v71, v71
	v_pk_mul_f32 v[54:55], v[72:73], v[54:55] op_sel_hi:[0,1]
	v_pk_mul_f32 v[60:61], v[72:73], v[60:61] op_sel_hi:[0,1]
	v_pk_mul_f32 v[62:63], v[72:73], v[62:63] op_sel_hi:[0,1]
	v_pk_mul_f32 v[52:53], v[72:73], v[52:53] op_sel_hi:[0,1]
	v_pk_mul_f32 v[54:55], v[58:59], v[54:55]
	v_pk_mul_f32 v[60:61], v[64:65], v[60:61]
	v_pk_mul_f32 v[62:63], v[66:67], v[62:63]
	v_pk_mul_f32 v[52:53], v[56:57], v[52:53]
	v_cvt_pk_bf16_f32 v56, v60, v61
	v_cvt_pk_bf16_f32 v57, v62, v63
	v_lshl_add_u64 v[68:69], v[68:69], 0, v[118:119]
	v_cvt_pk_bf16_f32 v58, v52, v53
	v_cvt_pk_bf16_f32 v55, v54, v55
	ds_bpermute_b32 v52, v120, v56
	ds_bpermute_b32 v53, v120, v57
	ds_bpermute_b32 v54, v120, v58
	ds_bpermute_b32 v55, v120, v55
	v_pk_mul_f32 v[16:17], v[12:13], v[16:17]
	v_pk_mul_f32 v[14:15], v[10:11], v[14:15]
	v_pk_mul_f32 v[4:5], v[8:9], v[4:5]
	s_andn2_b64 vcc, exec, s[38:39]
	s_waitcnt lgkmcnt(0)
	global_store_dwordx4 v[68:69], v[52:55], off
	ds_read_b32 v55, v122 offset:576
	s_waitcnt lgkmcnt(0)
	v_mul_f32_e32 v56, v55, v55
	v_mul_f32_e32 v54, 0xbfb8aa3b, v55
	v_pk_mul_f32 v[38:39], v[38:39], v[54:55] op_sel_hi:[1,0]
	v_pk_mul_f32 v[44:45], v[44:45], v[54:55] op_sel_hi:[1,0]
	v_pk_mul_f32 v[46:47], v[46:47], v[54:55] op_sel_hi:[1,0]
	v_pk_mul_f32 v[36:37], v[36:37], v[54:55] op_sel_hi:[1,0]
	v_exp_f32_e32 v38, v38
	v_exp_f32_e32 v39, v39
	v_exp_f32_e32 v44, v44
	v_exp_f32_e32 v45, v45
	v_exp_f32_e32 v46, v46
	v_exp_f32_e32 v47, v47
	v_exp_f32_e32 v36, v36
	v_exp_f32_e32 v37, v37
	v_pk_add_f32 v[38:39], v[38:39], 1.0 op_sel_hi:[1,0]
	v_pk_add_f32 v[44:45], v[44:45], 1.0 op_sel_hi:[1,0]
	v_pk_add_f32 v[46:47], v[46:47], 1.0 op_sel_hi:[1,0]
	v_pk_add_f32 v[36:37], v[36:37], 1.0 op_sel_hi:[1,0]
	v_rcp_f32_e32 v38, v38
	v_rcp_f32_e32 v39, v39
	v_rcp_f32_e32 v44, v44
	v_rcp_f32_e32 v45, v45
	v_rcp_f32_e32 v46, v46
	v_rcp_f32_e32 v47, v47
	v_rcp_f32_e32 v36, v36
	v_rcp_f32_e32 v37, v37
	v_pk_mul_f32 v[38:39], v[56:57], v[38:39] op_sel_hi:[0,1]
	v_pk_mul_f32 v[44:45], v[56:57], v[44:45] op_sel_hi:[0,1]
	v_pk_mul_f32 v[46:47], v[56:57], v[46:47] op_sel_hi:[0,1]
	v_pk_mul_f32 v[36:37], v[56:57], v[36:37] op_sel_hi:[0,1]
	v_pk_mul_f32 v[38:39], v[42:43], v[38:39]
	v_pk_mul_f32 v[44:45], v[48:49], v[44:45]
	v_pk_mul_f32 v[46:47], v[50:51], v[46:47]
	v_pk_mul_f32 v[36:37], v[40:41], v[36:37]
	v_cvt_pk_bf16_f32 v40, v44, v45
	v_cvt_pk_bf16_f32 v41, v46, v47
	v_add_u32_e32 v52, 0x90, v121
	v_cvt_pk_bf16_f32 v42, v36, v37
	v_cvt_pk_bf16_f32 v39, v38, v39
	ds_bpermute_b32 v36, v120, v40
	ds_bpermute_b32 v37, v120, v41
	ds_bpermute_b32 v38, v120, v42
	ds_bpermute_b32 v39, v120, v39
	v_mad_i64_i32 v[52:53], s[8:9], v52, s11, v[116:117]
	v_lshl_add_u64 v[52:53], v[52:53], 0, v[118:119]
	s_waitcnt lgkmcnt(0)
	global_store_dwordx4 v[52:53], v[36:39], off
	ds_read_b32 v39, v122 offset:640
	s_nop 0
	v_add_u32_e32 v36, 0xa0, v121
	v_mad_i64_i32 v[36:37], s[8:9], v36, s11, v[116:117]
	v_lshl_add_u64 v[36:37], v[36:37], 0, v[118:119]
	s_waitcnt lgkmcnt(0)
	v_mul_f32_e32 v38, 0xbfb8aa3b, v39
	v_pk_mul_f32 v[20:21], v[20:21], v[38:39] op_sel_hi:[1,0]
	v_pk_mul_f32 v[26:27], v[26:27], v[38:39] op_sel_hi:[1,0]
	v_pk_mul_f32 v[28:29], v[28:29], v[38:39] op_sel_hi:[1,0]
	v_pk_mul_f32 v[18:19], v[18:19], v[38:39] op_sel_hi:[1,0]
	v_exp_f32_e32 v20, v20
	v_exp_f32_e32 v21, v21
	v_exp_f32_e32 v26, v26
	v_exp_f32_e32 v27, v27
	v_exp_f32_e32 v28, v28
	v_exp_f32_e32 v29, v29
	v_exp_f32_e32 v18, v18
	v_exp_f32_e32 v19, v19
	v_pk_add_f32 v[20:21], v[20:21], 1.0 op_sel_hi:[1,0]
	v_pk_add_f32 v[26:27], v[26:27], 1.0 op_sel_hi:[1,0]
	v_pk_add_f32 v[28:29], v[28:29], 1.0 op_sel_hi:[1,0]
	v_pk_add_f32 v[18:19], v[18:19], 1.0 op_sel_hi:[1,0]
	v_rcp_f32_e32 v20, v20
	v_rcp_f32_e32 v21, v21
	v_rcp_f32_e32 v26, v26
	v_rcp_f32_e32 v27, v27
	v_rcp_f32_e32 v28, v28
	v_rcp_f32_e32 v29, v29
	v_rcp_f32_e32 v18, v18
	v_rcp_f32_e32 v19, v19
	v_mul_f32_e32 v40, v39, v39
	v_pk_mul_f32 v[20:21], v[40:41], v[20:21] op_sel_hi:[0,1]
	v_pk_mul_f32 v[26:27], v[40:41], v[26:27] op_sel_hi:[0,1]
	v_pk_mul_f32 v[28:29], v[40:41], v[28:29] op_sel_hi:[0,1]
	v_pk_mul_f32 v[18:19], v[40:41], v[18:19] op_sel_hi:[0,1]
	v_pk_mul_f32 v[20:21], v[24:25], v[20:21]
	v_pk_mul_f32 v[26:27], v[30:31], v[26:27]
	v_pk_mul_f32 v[28:29], v[32:33], v[28:29]
	v_pk_mul_f32 v[18:19], v[22:23], v[18:19]
	v_cvt_pk_bf16_f32 v22, v26, v27
	v_cvt_pk_bf16_f32 v23, v28, v29
	s_nop 0
	v_cvt_pk_bf16_f32 v24, v18, v19
	v_cvt_pk_bf16_f32 v21, v20, v21
	ds_bpermute_b32 v18, v120, v22
	ds_bpermute_b32 v19, v120, v23
	ds_bpermute_b32 v20, v120, v24
	ds_bpermute_b32 v21, v120, v21
	s_waitcnt lgkmcnt(0)
	global_store_dwordx4 v[36:37], v[18:21], off
	ds_read_b32 v21, v122 offset:704
	s_nop 0
	v_add_u32_e32 v18, 0xb0, v121
	v_mad_i64_i32 v[18:19], s[8:9], v18, s11, v[116:117]
	v_lshl_add_u64 v[18:19], v[18:19], 0, v[118:119]
	s_waitcnt lgkmcnt(0)
	v_mul_f32_e32 v20, 0xbfb8aa3b, v21
	v_pk_mul_f32 v[6:7], v[6:7], v[20:21] op_sel_hi:[1,0]
	v_mul_f32_e32 v22, v21, v21
	v_exp_f32_e32 v6, v6
	v_exp_f32_e32 v7, v7
	v_pk_mul_f32 v[10:11], v[10:11], v[20:21] op_sel_hi:[1,0]
	v_pk_mul_f32 v[12:13], v[12:13], v[20:21] op_sel_hi:[1,0]
	v_exp_f32_e32 v10, v10
	v_pk_add_f32 v[6:7], v[6:7], 1.0 op_sel_hi:[1,0]
	v_exp_f32_e32 v11, v11
	v_rcp_f32_e32 v6, v6
	v_rcp_f32_e32 v7, v7
	v_exp_f32_e32 v12, v12
	v_exp_f32_e32 v13, v13
	v_pk_add_f32 v[10:11], v[10:11], 1.0 op_sel_hi:[1,0]
	v_pk_mul_f32 v[6:7], v[22:23], v[6:7] op_sel_hi:[0,1]
	v_pk_mul_f32 v[2:3], v[2:3], v[6:7]
	v_pk_mul_f32 v[6:7], v[8:9], v[20:21] op_sel_hi:[1,0]
	v_pk_add_f32 v[12:13], v[12:13], 1.0 op_sel_hi:[1,0]
	v_exp_f32_e32 v6, v6
	v_exp_f32_e32 v7, v7
	v_rcp_f32_e32 v10, v10
	v_rcp_f32_e32 v11, v11
	v_rcp_f32_e32 v12, v12
	v_pk_add_f32 v[6:7], v[6:7], 1.0 op_sel_hi:[1,0]
	v_rcp_f32_e32 v13, v13
	v_rcp_f32_e32 v6, v6
	v_rcp_f32_e32 v7, v7
	v_pk_mul_f32 v[10:11], v[22:23], v[10:11] op_sel_hi:[0,1]
	v_pk_mul_f32 v[12:13], v[22:23], v[12:13] op_sel_hi:[0,1]
	v_pk_mul_f32 v[10:11], v[14:15], v[10:11]
	v_pk_mul_f32 v[6:7], v[22:23], v[6:7] op_sel_hi:[0,1]
	v_pk_mul_f32 v[4:5], v[4:5], v[6:7]
	v_pk_mul_f32 v[12:13], v[16:17], v[12:13]
	v_cvt_pk_bf16_f32 v6, v10, v11
	s_mov_b64 s[8:9], -1
	v_cvt_pk_bf16_f32 v7, v12, v13
	v_cvt_pk_bf16_f32 v8, v2, v3
	v_cvt_pk_bf16_f32 v5, v4, v5
	ds_bpermute_b32 v2, v120, v6
	ds_bpermute_b32 v3, v120, v7
	ds_bpermute_b32 v4, v120, v8
	ds_bpermute_b32 v5, v120, v5
	s_waitcnt lgkmcnt(0)
	global_store_dwordx4 v[18:19], v[2:5], off
	s_cbranch_vccnz .LBB0_1110
	s_andn2_b64 vcc, exec, s[4:5]
	s_cbranch_vccnz .LBB0_1109
	s_barrier
	s_branch .LBB0_1109
